# loop-edge edit: next-union-block SALU search and branch ladder moved from after the attention step barrier to before it (both half-steps)
# baseline (speedup 1.0000x reference)
.LBB0_1465:
	s_cmp_lt_i32 s9, 1
	s_mov_b32 s18, -1
	s_cbranch_scc1 .LBB0_1470
	s_min_u32 s17, s9, 0x80
	s_add_i32 s16, s17, -1
	s_cmp_lt_u32 s16, 64
	s_cselect_b64 s[0:1], -1, 0
	s_and_b64 vcc, exec, s[0:1]
	s_cbranch_vccnz .LBB0_1468
	s_addk_i32 s17, 0xffbf
	s_lshl_b64 s[0:1], 2, s17
	s_add_u32 s0, s0, -1
	s_addc_u32 s1, s1, -1
	s_and_b64 s[16:17], s[0:1], s[14:15]
	s_cmp_eq_u64 s[16:17], 0
	s_flbit_i32_b64 s16, s[16:17]
	s_cselect_b64 s[0:1], -1, 0
	s_xor_b32 s18, s16, 0x7f
	s_mov_b32 s16, 63
	s_andn2_b64 vcc, exec, s[0:1]
	s_cbranch_vccz .LBB0_1469
	s_branch .LBB0_1470

.LBB0_1470:
	s_cmp_lt_i32 s7, 0
	s_mov_b64 s[0:1], -1
	s_waitcnt lgkmcnt(0)
	s_barrier
	s_cbranch_scc1 .LBB0_1457
	s_max_i32 s0, s18, 0
	s_lshl_b32 s76, s0, 6
	s_mul_i32 s98, s0, 0x30000
	s_mov_b32 s99, 0
	v_lshl_add_u64 v[22:23], v[250:251], 0, s[98:99]
	global_load_dwordx4 v[18:21], v[22:23], off offset:1024
	s_nop 0
	global_load_dwordx4 v[22:25], v[22:23], off offset:1152
	s_max_i32 s98, s9, 0
	s_lshr_b32 s98, s98, 3
	s_and_b32 s98, s98, 0x1ffffffc
	v_add_u32_e32 v244, s98, v157
	ds_read_b32 v242, v244 offset:16
	s_and_b32 s16, s7, 31
	v_bfe_u32 v74, v243, s16, 1
	v_cmp_ne_u32_e32 vcc, 0, v74
	s_mov_b64 s[0:1], vcc
	s_cbranch_vccz .LBB0_1475
	ds_read_b128 v[120:123], v117
	ds_read_b128 v[124:127], v117 offset:2560
	ds_read_b128 v[128:131], v117 offset:5120
	ds_read_b128 v[132:135], v117 offset:7680
	ds_read_b128 v[136:139], v117 offset:64
	ds_read_b128 v[140:143], v117 offset:2624
	ds_read_b128 v[176:179], v117 offset:5184
	ds_read_b128 v[180:183], v117 offset:7744
	v_lshl_add_u32 v74, s7, 6, v111
	v_cvt_f32_i32_e32 v90, v74
	v_fma_f32 v74, v146, v90, -v109
	v_fma_f32 v90, v148, v90, -v110
	v_cndmask_b32_e64 v89, v173, v74, s[0:1]
	v_cndmask_b32_e64 v105, v173, v90, s[0:1]
	v_fma_f32 v74, v146, s77, v89
	v_fma_f32 v75, v146, s95, v89
	v_fma_f32 v76, v146, s4, v89
	v_fma_f32 v77, v146, s5, v89
	v_fma_f32 v78, v146, s86, v89
	v_fma_f32 v79, v146, s87, v89
	v_fma_f32 v80, v146, s84, v89
	v_fma_f32 v81, v146, s85, v89
	v_fma_f32 v82, v146, s88, v89
	v_fma_f32 v83, v146, s89, v89
	v_fma_f32 v84, v146, s90, v89
	v_fma_f32 v85, v146, s91, v89
	v_fma_f32 v86, v146, s72, v89
	v_fma_f32 v87, v146, s73, v89
	v_fma_f32 v88, v146, s74, v89
	v_fma_f32 v89, v146, s75, v89
	v_fma_f32 v90, v148, s77, v105
	v_fma_f32 v91, v148, s95, v105
	v_fma_f32 v92, v148, s4, v105
	v_fma_f32 v93, v148, s5, v105
	v_fma_f32 v94, v148, s86, v105
	v_fma_f32 v95, v148, s87, v105
	v_fma_f32 v96, v148, s84, v105
	v_fma_f32 v97, v148, s85, v105
	v_fma_f32 v98, v148, s88, v105
	v_fma_f32 v99, v148, s89, v105
	v_fma_f32 v100, v148, s90, v105
	v_fma_f32 v101, v148, s91, v105
	v_fma_f32 v102, v148, s72, v105
	v_fma_f32 v103, v148, s73, v105
	v_fma_f32 v104, v148, s74, v105
	v_fma_f32 v105, v148, s75, v105
	s_setprio 1
	s_waitcnt lgkmcnt(7)
	v_mfma_f32_16x16x32_bf16 v[74:77], v[120:123], v[6:9], v[74:77]
	v_mfma_f32_16x16x32_bf16 v[90:93], v[120:123], v[14:17], v[90:93]
	s_waitcnt lgkmcnt(6)
	v_mfma_f32_16x16x32_bf16 v[78:81], v[124:127], v[6:9], v[78:81]
	v_mfma_f32_16x16x32_bf16 v[94:97], v[124:127], v[14:17], v[94:97]
	s_waitcnt lgkmcnt(5)
	v_mfma_f32_16x16x32_bf16 v[120:123], v[128:131], v[6:9], v[82:85]
	v_mfma_f32_16x16x32_bf16 v[124:127], v[128:131], v[14:17], v[98:101]
	s_waitcnt lgkmcnt(4)
	v_mfma_f32_16x16x32_bf16 v[128:131], v[132:135], v[6:9], v[86:89]
	v_mfma_f32_16x16x32_bf16 v[132:135], v[132:135], v[14:17], v[102:105]
	s_waitcnt lgkmcnt(3)
	v_mfma_f32_16x16x32_bf16 v[102:105], v[136:139], v[2:5], v[74:77]
	v_mfma_f32_16x16x32_bf16 v[86:89], v[136:139], v[10:13], v[90:93]
	s_waitcnt lgkmcnt(2)
	v_mfma_f32_16x16x32_bf16 v[98:101], v[140:143], v[2:5], v[78:81]
	v_mfma_f32_16x16x32_bf16 v[82:85], v[140:143], v[10:13], v[94:97]
	s_waitcnt lgkmcnt(1)
	v_mfma_f32_16x16x32_bf16 v[94:97], v[176:179], v[2:5], v[120:123]
	v_mfma_f32_16x16x32_bf16 v[78:81], v[176:179], v[10:13], v[124:127]
	s_waitcnt lgkmcnt(0)
	v_mfma_f32_16x16x32_bf16 v[90:93], v[180:183], v[2:5], v[128:131]
	v_mfma_f32_16x16x32_bf16 v[74:77], v[180:183], v[10:13], v[132:135]
	s_setprio 0
	v_max3_f32 v120, v102, s96, v103
	v_max3_f32 v120, v120, v104, v105
	v_max3_f32 v120, v120, v98, v99
	v_max3_f32 v120, v120, v100, v101
	v_max3_f32 v120, v120, v94, v95
	v_max3_f32 v120, v120, v96, v97
	v_max3_f32 v120, v120, v90, v91
	v_max3_f32 v121, v120, v92, v93
	v_max3_f32 v120, v121, v86, v87
	v_max3_f32 v120, v120, v88, v89
	v_max3_f32 v120, v120, v82, v83
	v_max3_f32 v120, v120, v84, v85
	v_max3_f32 v120, v120, v78, v79
	v_max3_f32 v120, v120, v80, v81
	v_max3_f32 v120, v120, v74, v75
	v_max3_f32 v120, v120, v76, v77
	s_mov_b32 s0, 0x41000000
	v_cmp_lt_f32_e32 vcc, s0, v120
	s_cbranch_vccnz .LBB0_1483
	v_cmp_lt_f32_e32 vcc, s94, v120
	s_cbranch_vccz .LBB0_1475

.LBB0_1477:
	s_cmp_lt_i32 s18, 1
	s_mov_b32 s19, -1
	s_cbranch_scc1 .Lmy_bar2
	s_add_i32 s7, s18, -1
	s_cmp_lt_u32 s7, 64
	s_cselect_b64 s[16:17], -1, 0
	s_and_b64 vcc, exec, s[16:17]
	s_cbranch_vccnz .LBB0_1480
	s_add_i32 s7, s18, 0xffffffbf
	s_lshl_b64 s[16:17], 2, s7
	s_add_u32 s16, s16, -1
	s_addc_u32 s17, s17, -1
	s_and_b64 s[22:23], s[16:17], s[14:15]
	s_cmp_eq_u64 s[22:23], 0
	s_flbit_i32_b64 s7, s[22:23]
	s_cselect_b64 s[16:17], -1, 0
	s_xor_b32 s19, s7, 0x7f
	s_mov_b32 s7, 63
	s_andn2_b64 vcc, exec, s[16:17]
	s_cbranch_vccnz .Lmy_bar2
	s_branch .LBB0_1481

.Lmy_bar2:
	s_waitcnt lgkmcnt(0)
	s_barrier
	s_branch .LBB0_1458
